# v26: v22 + attention tile-(i+2) global loads issued after QK instead of at the loop top
# baseline (speedup 1.0000x reference)
; #define ATT_PV(VBUF) do { s16x4 vlo[4], vhi[4]; ATT_PV_PRE(VBUF); ATT_PV_RUN(VBUF); } while (0)
; template <int PM> DI void attn_phase(const Params& p, int l, char* smem, int* s_item, int wv, int cidx) {
;     ...
;         if (PM != 2 && i + 2 < ntl) {
;           const int inx = i + 2;
;           const int Rn = (inx < nplain) ? Rb + 64 * inx : Rb + 256 + local_t0 + 64 * (inx - nplain);
;           const u16* nbase = p.P + (size_t)(Rn + trow) * INW + tch * 8;
; #pragma unroll
;           for (int j = 0; j < 2; ++j) {
;             kst[j] = *(const u32x4*)(nbase + (size_t)j * 32 * INW + koff);
;             vst[j] = *(const u32x4*)(nbase + (size_t)j * 32 * INW + voff);
;           }
;         }
;         __builtin_amdgcn_sched_barrier(0);
;         if (shift && pend) { ATT_PV(vprev); pend = false; }
;         bool active = (PM != 1);
;         const int tpos = local_t0 + 64 * (i - nplain);
;         if (i >= nplain) {
;           if (mode == 1) active = (PM != 1) && (tpos + 63 >= tq0 - 128) && (tpos <= tq0 + 31 + 128);
;           else { const int dr = (tpos >> 6) - kr0; active = (PM != 1) && (dr >= 0 && dr < 8); }
;         }
.LBB0_424:
.LBB0_430:
	s_cmp_ge_u32 s2, s80
	s_cselect_b64 s[0:1], -1, 0
	s_cmp_lt_u32 s2, s80
	s_mov_b64 s[2:3], -1
	s_cbranch_scc1 .LBB0_435
	s_mov_b64 s[74:75], -1
	s_and_b64 vcc, exec, s[78:79]
	s_cbranch_vccz .LBB0_433
	s_ashr_i32 s2, s92, 6
	s_sub_i32 s2, s2, s83
	s_cmp_lt_u32 s2, 8
	s_mov_b64 s[74:75], 0
	s_cselect_b64 s[2:3], -1, 0

; template <int PM> DI void attn_phase(const Params& p, int l, char* smem, int* s_item, int wv, int cidx) {
;     ...
;         if (PM != 2 && i + 2 < ntl) {
;           const int inx = i + 2;
;           const int Rn = (inx < nplain) ? Rb + 64 * inx : Rb + 256 + local_t0 + 64 * (inx - nplain);
;           const u16* nbase = p.P + (size_t)(Rn + trow) * INW + tch * 8;
; #pragma unroll
;           for (int j = 0; j < 2; ++j) {
;             kst[j] = *(const u32x4*)(nbase + (size_t)j * 32 * INW + koff);
;             vst[j] = *(const u32x4*)(nbase + (size_t)j * 32 * INW + voff);
;           }
;         }
.LBB0_441:
	s_add_i32 s3, s94, 1
	s_cmp_ge_i32 s3, s81
	s_cbranch_scc1 .Lmv_nold
	s_lshl_b32 s2, s3, 6
	s_add_i32 s2, s2, s84
	s_add_i32 vcc_lo, s90, s92
	s_cmp_ge_u32 s3, s80
	s_cselect_b32 s2, vcc_lo, s2
	v_add_u32_e32 v0, s2, v239
	v_mad_i64_i32 v[2:3], vcc, v0, s85, v[202:203]
	v_lshl_add_u64 v[4:5], v[2:3], 0, s[96:97]
	v_lshl_add_u64 v[6:7], v[2:3], 0, s[76:77]
	v_lshl_add_u64 v[2:3], v[2:3], 0, s[98:99]
	global_load_dwordx4 v[180:183], v[4:5], off
	global_load_dwordx4 v[184:187], v[6:7], off
	v_lshl_add_u64 v[4:5], v[2:3], 0, s[96:97]
	v_lshl_add_u64 v[2:3], v[2:3], 0, s[76:77]
	global_load_dwordx4 v[188:191], v[4:5], off
	global_load_dwordx4 v[192:195], v[2:3], off
